# scan loop: four operand register sets with 3-step prefetch, one counted LDS wait per two steps (16 instead of 32 per chunk)
# baseline (speedup 1.0000x reference)
; __device__ void scan_block(const Params& P, int sb, unsigned char* lds) {
;     ...
;     __builtin_amdgcn_s_setprio(2);
;     __syncthreads();
;     for (int c = 0; c < NCH; ++c) {
;       const float* b = buf + (c & 1) * SC_STAGE;
;       const float* q = b + ks * 4;
;       const float* qv = b + 320 + myrow;
;       float* yo = Y + (size_t)(c * SC_CH + ks) * 1024 + hb + rg * 16 + myrow;
;       f32x4 w4 = *(const f32x4*)(q), k4 = *(const f32x4*)(q + 64), b4 = *(const f32x4*)(q + 128), kh4 = *(const f32x4*)(q + 192), r4 = *(const f32x4*)(q + 256);
;       float v = qv[0];
;       float yk = 0.f, ypart = 0.f;
; #pragma unroll
;       for (int s = 0; s < SC_CH; ++s) {
;         f32x4 w4n, k4n, b4n, kh4n, r4n; float vn;
;         if (s + 1 < SC_CH) {
;           const float* qn = q + (s + 1) * SC_STEP;
;           w4n = *(const f32x4*)(qn); k4n = *(const f32x4*)(qn + 64); b4n = *(const f32x4*)(qn + 128); kh4n = *(const f32x4*)(qn + 192); r4n = *(const f32x4*)(qn + 256);
;           vn = qv[(s + 1) * SC_STEP];
;         }
;         __builtin_amdgcn_sched_barrier(0);
;         if (s > 0) {
;           const float y = dpp_allreduce16(ypart);
;           yk = (ks == ((s - 1) & 15)) ? y : yk;
;           if (((s - 1) & 15) == 15) yo[(size_t)(s - 16) * 1024] = yk;
;         }
;         const f32x2 pp = (f32x2){S[0], S[1]} * (f32x2){k4[0], k4[1]} + (f32x2){S[2], S[3]} * (f32x2){k4[2], k4[3]};
;         const f32x4 A = S * w4 + v * kh4;
;         const float ar = dpp_allreduce16(pp.x + pp.y);
;         S = A + ar * b4;
;         const f32x2 yy = (f32x2){S[0], S[1]} * (f32x2){r4[0], r4[1]} + (f32x2){S[2], S[3]} * (f32x2){r4[2], r4[3]};
;         ypart = yy.x + yy.y;
;         if (s + 1 < SC_CH) { w4 = w4n; k4 = k4n; b4 = b4n; kh4 = kh4n; r4 = r4n; v = vn; }
.LBB0_50:
	s_andn2_b64 vcc, exec, s[8:9]
	v_readlane_b32 s3, v252, 9
	s_cbranch_vccnz .LBB0_150
	v_readlane_b32 s2, v252, 0
	v_mov_b32_e32 v149, v169
	s_movk_i32 s0, 0x100
	s_nop 0
	v_cmp_gt_i32_e32 vcc, s0, v149
	s_lshl_b32 s0, s2, 4
	s_and_b32 s12, s0, 0xffffffc0
	s_barrier
	s_and_saveexec_b64 s[0:1], vcc
	s_xor_b64 s[82:83], exec, s[0:1]
	s_cbranch_execz .LBB0_55
	s_mov_b64 s[90:91], s[62:63]
	v_bfe_u32 v8, v149, 4, 4
	v_and_b32_e32 v0, 15, v149
	s_setprio 2
	s_ashr_i32 s13, s12, 31
	s_and_b32 s6, s2, 3
	s_lshl_b32 s8, s6, 6
	s_lshl_b64 s[6:7], s[12:13], 2
	s_add_u32 s6, s6, s8
	s_addc_u32 s7, s7, 0
	v_readlane_b32 s4, v251, 36
	v_readlane_b32 s5, v251, 37
	v_and_b32_e32 v2, 2, v0
	v_and_b32_e32 v3, 1, v0
	s_add_u32 s4, s4, s6
	s_addc_u32 s5, s5, s7
	v_cmp_ne_u32_e64 s[40:41], 0, v2
	v_cmp_ne_u32_e64 s[42:43], 0, v3
	v_lshl_add_u32 v9, v0, 4, 16
	v_lshl_add_u32 v10, v8, 2, 16
	v_bfrev_b32_e32 v2, v0
	v_lshrrev_b32_e32 v2, 16, v2
	v_lshl_add_u32 v2, v8, 2, v2
	v_add_u32_e32 v3, 0x10000, v2
	v_mov_b32_e32 v4, 0
	v_mov_b32_e32 v5, 0
	v_mov_b32_e32 v6, 0
	v_mov_b32_e32 v7, 0
	s_mov_b32 s3, 0
	s_waitcnt vmcnt(0)
	s_barrier
	ds_read_b128 v[12:15], v9 offset:256
	ds_read_b128 v[16:19], v9 offset:0
	ds_read_b128 v[20:23], v9 offset:768
	ds_read_b32 v24, v10 offset:1280
	ds_read_b128 v[44:47], v9 offset:512
	ds_read_b128 v[60:63], v9 offset:1600
	ds_read_b128 v[64:67], v9 offset:1344
	ds_read_b128 v[28:31], v9 offset:2112
	ds_read_b32 v32, v10 offset:2624
	ds_read_b128 v[48:51], v9 offset:1856
	ds_read_b128 v[36:39], v9 offset:1024
	ds_read_b128 v[68:71], v9 offset:2944
	ds_read_b128 v[72:75], v9 offset:2688
	ds_read_b128 v[84:87], v9 offset:3456
	ds_read_b32 v92, v10 offset:3968
	ds_read_b128 v[104:107], v9 offset:3200
	ds_read_b128 v[40:43], v9 offset:2368
.Lscan_top:
	s_waitcnt lgkmcnt(6)
	v_pk_mul_f32 v[52:53], v[6:7], v[14:15]
	v_pk_mul_f32 v[56:57], v[6:7], v[18:19]
	v_pk_fma_f32 v[52:53], v[4:5], v[12:13], v[52:53]
	v_pk_mul_f32 v[54:55], v[4:5], v[16:17]
	v_add_f32_e32 v52, v52, v53
	ds_read_b128 v[76:79], v9 offset:4288
	ds_read_b128 v[80:83], v9 offset:4032
	v_add_f32_dpp v52, v52, v52 quad_perm:[1,0,3,2] row_mask:0xf bank_mask:0xf bound_ctrl:1
	v_pk_fma_f32 v[56:57], v[22:23], v[24:25], v[56:57] op_sel_hi:[1,0,1]
	v_pk_fma_f32 v[54:55], v[20:21], v[24:25], v[54:55] op_sel_hi:[1,0,1]
	v_add_f32_dpp v52, v52, v52 quad_perm:[2,3,0,1] row_mask:0xf bank_mask:0xf bound_ctrl:1
	ds_read_b128 v[88:91], v9 offset:4800
	ds_read_b32 v94, v10 offset:5312
	v_add_f32_dpp v52, v52, v52 row_half_mirror row_mask:0xf bank_mask:0xf bound_ctrl:1
	s_nop 1
	v_add_f32_dpp v52, v52, v52 row_mirror row_mask:0xf bank_mask:0xf bound_ctrl:1
	v_pk_fma_f32 v[6:7], v[46:47], v[52:53], v[56:57] op_sel_hi:[1,0,1]
	v_pk_fma_f32 v[4:5], v[44:45], v[52:53], v[54:55] op_sel_hi:[1,0,1]
	ds_read_b128 v[96:99], v9 offset:3712
	ds_read_b128 v[108:111], v9 offset:4544
	v_pk_mul_f32 v[52:53], v[6:7], v[62:63]
	v_pk_mul_f32 v[56:57], v[6:7], v[66:67]
	v_pk_fma_f32 v[52:53], v[4:5], v[60:61], v[52:53]
	v_pk_mul_f32 v[54:55], v[4:5], v[64:65]
	v_add_f32_e32 v52, v52, v53
	ds_read_b128 v[12:15], v9 offset:5632
	ds_read_b128 v[16:19], v9 offset:5376
	v_add_f32_dpp v52, v52, v52 quad_perm:[1,0,3,2] row_mask:0xf bank_mask:0xf bound_ctrl:1
	v_pk_fma_f32 v[56:57], v[30:31], v[32:33], v[56:57] op_sel_hi:[1,0,1]
	v_pk_fma_f32 v[54:55], v[28:29], v[32:33], v[54:55] op_sel_hi:[1,0,1]
	v_add_f32_dpp v52, v52, v52 quad_perm:[2,3,0,1] row_mask:0xf bank_mask:0xf bound_ctrl:1
	ds_read_b128 v[20:23], v9 offset:6144
	ds_read_b32 v24, v10 offset:6656
	v_add_f32_dpp v52, v52, v52 row_half_mirror row_mask:0xf bank_mask:0xf bound_ctrl:1
	v_pk_mul_f32 v[26:27], v[6:7], v[38:39]
	s_nop 0
	v_add_f32_dpp v52, v52, v52 row_mirror row_mask:0xf bank_mask:0xf bound_ctrl:1
	v_pk_fma_f32 v[6:7], v[50:51], v[52:53], v[56:57] op_sel_hi:[1,0,1]
	v_pk_fma_f32 v[26:27], v[4:5], v[36:37], v[26:27]
	v_pk_fma_f32 v[4:5], v[48:49], v[52:53], v[54:55] op_sel_hi:[1,0,1]
	ds_read_b128 v[100:103], v9 offset:5056
	ds_read_b128 v[44:47], v9 offset:5888
	v_add_f32_e32 v25, v26, v27
	s_waitcnt lgkmcnt(6)
	v_pk_mul_f32 v[52:53], v[6:7], v[70:71]
	v_pk_mul_f32 v[56:57], v[6:7], v[74:75]
	v_pk_fma_f32 v[52:53], v[4:5], v[68:69], v[52:53]
	v_pk_mul_f32 v[54:55], v[4:5], v[72:73]
	v_add_f32_e32 v52, v52, v53
	ds_read_b128 v[60:63], v9 offset:6976
	ds_read_b128 v[64:67], v9 offset:6720
	v_add_f32_dpp v52, v52, v52 quad_perm:[1,0,3,2] row_mask:0xf bank_mask:0xf bound_ctrl:1
	v_pk_fma_f32 v[56:57], v[86:87], v[92:93], v[56:57] op_sel_hi:[1,0,1]
	v_pk_fma_f32 v[54:55], v[84:85], v[92:93], v[54:55] op_sel_hi:[1,0,1]
	v_add_f32_dpp v52, v52, v52 quad_perm:[2,3,0,1] row_mask:0xf bank_mask:0xf bound_ctrl:1
	ds_read_b128 v[28:31], v9 offset:7488
	ds_read_b32 v32, v10 offset:8000
	v_add_f32_dpp v52, v52, v52 row_half_mirror row_mask:0xf bank_mask:0xf bound_ctrl:1
	v_pk_mul_f32 v[26:27], v[6:7], v[42:43]
	v_add_f32_dpp v34, v25, v25 row_ror:8 row_mask:0xf bank_mask:0x3
	v_add_f32_dpp v52, v52, v52 row_mirror row_mask:0xf bank_mask:0xf bound_ctrl:1
	v_pk_fma_f32 v[6:7], v[106:107], v[52:53], v[56:57] op_sel_hi:[1,0,1]
	v_pk_fma_f32 v[26:27], v[4:5], v[40:41], v[26:27]
	v_pk_fma_f32 v[4:5], v[104:105], v[52:53], v[54:55] op_sel_hi:[1,0,1]
	ds_read_b128 v[36:39], v9 offset:6400
	ds_read_b128 v[48:51], v9 offset:7232
	v_add_f32_e32 v25, v26, v27
	v_pk_mul_f32 v[52:53], v[6:7], v[78:79]
	v_pk_mul_f32 v[56:57], v[6:7], v[82:83]
	v_pk_fma_f32 v[52:53], v[4:5], v[76:77], v[52:53]
	v_pk_mul_f32 v[54:55], v[4:5], v[80:81]
	v_add_f32_e32 v52, v52, v53
	ds_read_b128 v[68:71], v9 offset:8320
	ds_read_b128 v[72:75], v9 offset:8064
	v_add_f32_dpp v52, v52, v52 quad_perm:[1,0,3,2] row_mask:0xf bank_mask:0xf bound_ctrl:1
	v_pk_fma_f32 v[56:57], v[90:91], v[94:95], v[56:57] op_sel_hi:[1,0,1]
	v_pk_fma_f32 v[54:55], v[88:89], v[94:95], v[54:55] op_sel_hi:[1,0,1]
	v_add_f32_dpp v52, v52, v52 quad_perm:[2,3,0,1] row_mask:0xf bank_mask:0xf bound_ctrl:1
	ds_read_b128 v[84:87], v9 offset:8832
	ds_read_b32 v92, v10 offset:9344
	v_add_f32_dpp v52, v52, v52 row_half_mirror row_mask:0xf bank_mask:0xf bound_ctrl:1
	v_pk_mul_f32 v[26:27], v[6:7], v[98:99]
	v_add_f32_dpp v34, v25, v25 row_ror:8 row_mask:0xf bank_mask:0xc
	v_add_f32_dpp v52, v52, v52 row_mirror row_mask:0xf bank_mask:0xf bound_ctrl:1
	v_pk_fma_f32 v[6:7], v[110:111], v[52:53], v[56:57] op_sel_hi:[1,0,1]
	v_pk_fma_f32 v[26:27], v[4:5], v[96:97], v[26:27]
	v_pk_fma_f32 v[4:5], v[108:109], v[52:53], v[54:55] op_sel_hi:[1,0,1]
	ds_read_b128 v[40:43], v9 offset:7744
	ds_read_b128 v[104:107], v9 offset:8576
	v_add_f32_e32 v25, v26, v27
	v_add_f32_dpp v35, v34, v34 row_half_mirror row_mask:0xf bank_mask:0x5
	s_waitcnt lgkmcnt(6)
; __device__ void scan_block(const Params& P, int sb, unsigned char* lds) {
;     ...
;       for (int s = 0; s < SC_CH; ++s) {
;         f32x4 w4n, k4n, b4n, kh4n, r4n; float vn;
;         if (s + 1 < SC_CH) {
;           const float* qn = q + (s + 1) * SC_STEP;
;           w4n = *(const f32x4*)(qn); k4n = *(const f32x4*)(qn + 64); b4n = *(const f32x4*)(qn + 128); kh4n = *(const f32x4*)(qn + 192); r4n = *(const f32x4*)(qn + 256);
;           vn = qv[(s + 1) * SC_STEP];
;         }
;         __builtin_amdgcn_sched_barrier(0);
;         if (s > 0) {
;           const float y = dpp_allreduce16(ypart);
;           yk = (ks == ((s - 1) & 15)) ? y : yk;
;           if (((s - 1) & 15) == 15) yo[(size_t)(s - 16) * 1024] = yk;
;         }
;         const f32x2 pp = (f32x2){S[0], S[1]} * (f32x2){k4[0], k4[1]} + (f32x2){S[2], S[3]} * (f32x2){k4[2], k4[3]};
;         const f32x4 A = S * w4 + v * kh4;
;         const float ar = dpp_allreduce16(pp.x + pp.y);
;         S = A + ar * b4;
;         const f32x2 yy = (f32x2){S[0], S[1]} * (f32x2){r4[0], r4[1]} + (f32x2){S[2], S[3]} * (f32x2){r4[2], r4[3]};
;         ypart = yy.x + yy.y;
;         if (s + 1 < SC_CH) { w4 = w4n; k4 = k4n; b4 = b4n; kh4 = kh4n; r4 = r4n; v = vn; }
	v_pk_mul_f32 v[52:53], v[6:7], v[14:15]
	v_pk_mul_f32 v[56:57], v[6:7], v[18:19]
	v_pk_fma_f32 v[52:53], v[4:5], v[12:13], v[52:53]
	v_pk_mul_f32 v[54:55], v[4:5], v[16:17]
	v_add_f32_e32 v52, v52, v53
	ds_read_b128 v[76:79], v9 offset:9664
	ds_read_b128 v[80:83], v9 offset:9408
	v_add_f32_dpp v52, v52, v52 quad_perm:[1,0,3,2] row_mask:0xf bank_mask:0xf bound_ctrl:1
	v_pk_fma_f32 v[56:57], v[22:23], v[24:25], v[56:57] op_sel_hi:[1,0,1]
	v_pk_fma_f32 v[54:55], v[20:21], v[24:25], v[54:55] op_sel_hi:[1,0,1]
	v_add_f32_dpp v52, v52, v52 quad_perm:[2,3,0,1] row_mask:0xf bank_mask:0xf bound_ctrl:1
	ds_read_b128 v[88:91], v9 offset:10176
	ds_read_b32 v94, v10 offset:10688
	v_add_f32_dpp v52, v52, v52 row_half_mirror row_mask:0xf bank_mask:0xf bound_ctrl:1
	v_pk_mul_f32 v[26:27], v[6:7], v[102:103]
	v_add_f32_dpp v34, v25, v25 row_ror:8 row_mask:0xf bank_mask:0x3
	v_add_f32_dpp v52, v52, v52 row_mirror row_mask:0xf bank_mask:0xf bound_ctrl:1
	v_pk_fma_f32 v[6:7], v[46:47], v[52:53], v[56:57] op_sel_hi:[1,0,1]
	v_pk_fma_f32 v[26:27], v[4:5], v[100:101], v[26:27]
	v_pk_fma_f32 v[4:5], v[44:45], v[52:53], v[54:55] op_sel_hi:[1,0,1]
	ds_read_b128 v[96:99], v9 offset:9088
	ds_read_b128 v[108:111], v9 offset:9920
	v_add_f32_e32 v25, v26, v27
	v_pk_mul_f32 v[52:53], v[6:7], v[62:63]
	v_pk_mul_f32 v[56:57], v[6:7], v[66:67]
	v_pk_fma_f32 v[52:53], v[4:5], v[60:61], v[52:53]
	v_pk_mul_f32 v[54:55], v[4:5], v[64:65]
	v_add_f32_e32 v52, v52, v53
	ds_read_b128 v[12:15], v9 offset:11008
	ds_read_b128 v[16:19], v9 offset:10752
	v_add_f32_dpp v52, v52, v52 quad_perm:[1,0,3,2] row_mask:0xf bank_mask:0xf bound_ctrl:1
	v_pk_fma_f32 v[56:57], v[30:31], v[32:33], v[56:57] op_sel_hi:[1,0,1]
	v_pk_fma_f32 v[54:55], v[28:29], v[32:33], v[54:55] op_sel_hi:[1,0,1]
	v_add_f32_dpp v52, v52, v52 quad_perm:[2,3,0,1] row_mask:0xf bank_mask:0xf bound_ctrl:1
	ds_read_b128 v[20:23], v9 offset:11520
	ds_read_b32 v24, v10 offset:12032
	v_add_f32_dpp v52, v52, v52 row_half_mirror row_mask:0xf bank_mask:0xf bound_ctrl:1
	v_pk_mul_f32 v[26:27], v[6:7], v[38:39]
	v_add_f32_dpp v34, v25, v25 row_ror:8 row_mask:0xf bank_mask:0xc
	v_add_f32_dpp v52, v52, v52 row_mirror row_mask:0xf bank_mask:0xf bound_ctrl:1
	v_pk_fma_f32 v[6:7], v[50:51], v[52:53], v[56:57] op_sel_hi:[1,0,1]
	v_pk_fma_f32 v[26:27], v[4:5], v[36:37], v[26:27]
	v_pk_fma_f32 v[4:5], v[48:49], v[52:53], v[54:55] op_sel_hi:[1,0,1]
	ds_read_b128 v[100:103], v9 offset:10432
	ds_read_b128 v[44:47], v9 offset:11264
	v_add_f32_e32 v25, v26, v27
	v_add_f32_dpp v35, v34, v34 row_half_mirror row_mask:0xf bank_mask:0xa
	s_waitcnt lgkmcnt(6)
	v_pk_mul_f32 v[52:53], v[6:7], v[70:71]
	v_pk_mul_f32 v[56:57], v[6:7], v[74:75]
	v_pk_fma_f32 v[52:53], v[4:5], v[68:69], v[52:53]
	v_pk_mul_f32 v[54:55], v[4:5], v[72:73]
	v_add_f32_e32 v52, v52, v53
	ds_read_b128 v[60:63], v9 offset:12352
	ds_read_b128 v[64:67], v9 offset:12096
	v_add_f32_dpp v52, v52, v52 quad_perm:[1,0,3,2] row_mask:0xf bank_mask:0xf bound_ctrl:1
	v_pk_fma_f32 v[56:57], v[86:87], v[92:93], v[56:57] op_sel_hi:[1,0,1]
	v_pk_fma_f32 v[54:55], v[84:85], v[92:93], v[54:55] op_sel_hi:[1,0,1]
	v_add_f32_dpp v52, v52, v52 quad_perm:[2,3,0,1] row_mask:0xf bank_mask:0xf bound_ctrl:1
	ds_read_b128 v[28:31], v9 offset:12864
	ds_read_b32 v32, v10 offset:13376
	v_add_f32_dpp v52, v52, v52 row_half_mirror row_mask:0xf bank_mask:0xf bound_ctrl:1
	v_pk_mul_f32 v[26:27], v[6:7], v[42:43]
	v_add_f32_dpp v34, v25, v25 row_ror:8 row_mask:0xf bank_mask:0x3
	v_add_f32_dpp v52, v52, v52 row_mirror row_mask:0xf bank_mask:0xf bound_ctrl:1
	v_pk_fma_f32 v[6:7], v[106:107], v[52:53], v[56:57] op_sel_hi:[1,0,1]
	v_pk_fma_f32 v[26:27], v[4:5], v[40:41], v[26:27]
	v_pk_fma_f32 v[4:5], v[104:105], v[52:53], v[54:55] op_sel_hi:[1,0,1]
	ds_read_b128 v[36:39], v9 offset:11776
	ds_read_b128 v[48:51], v9 offset:12608
	v_add_f32_e32 v25, v26, v27
	v_pk_mul_f32 v[52:53], v[6:7], v[78:79]
	v_pk_mul_f32 v[56:57], v[6:7], v[82:83]
	v_pk_fma_f32 v[52:53], v[4:5], v[76:77], v[52:53]
	v_pk_mul_f32 v[54:55], v[4:5], v[80:81]
	v_add_f32_e32 v52, v52, v53
	ds_read_b128 v[68:71], v9 offset:13696
	ds_read_b128 v[72:75], v9 offset:13440
	v_add_f32_dpp v52, v52, v52 quad_perm:[1,0,3,2] row_mask:0xf bank_mask:0xf bound_ctrl:1
	v_pk_fma_f32 v[56:57], v[90:91], v[94:95], v[56:57] op_sel_hi:[1,0,1]
	v_pk_fma_f32 v[54:55], v[88:89], v[94:95], v[54:55] op_sel_hi:[1,0,1]
	v_add_f32_dpp v52, v52, v52 quad_perm:[2,3,0,1] row_mask:0xf bank_mask:0xf bound_ctrl:1
	ds_read_b128 v[84:87], v9 offset:14208
	ds_read_b32 v92, v10 offset:14720
	v_add_f32_dpp v52, v52, v52 row_half_mirror row_mask:0xf bank_mask:0xf bound_ctrl:1
	v_pk_mul_f32 v[26:27], v[6:7], v[98:99]
	v_add_f32_dpp v34, v25, v25 row_ror:8 row_mask:0xf bank_mask:0xc
	v_add_f32_dpp v52, v52, v52 row_mirror row_mask:0xf bank_mask:0xf bound_ctrl:1
	v_pk_fma_f32 v[6:7], v[110:111], v[52:53], v[56:57] op_sel_hi:[1,0,1]
	v_pk_fma_f32 v[26:27], v[4:5], v[96:97], v[26:27]
	v_pk_fma_f32 v[4:5], v[108:109], v[52:53], v[54:55] op_sel_hi:[1,0,1]
	ds_read_b128 v[40:43], v9 offset:13120
	ds_read_b128 v[104:107], v9 offset:13952
	v_add_f32_e32 v25, v26, v27
	v_add_f32_dpp v58, v34, v34 row_half_mirror row_mask:0xf bank_mask:0x5
	s_waitcnt lgkmcnt(6)
; __device__ void scan_block(const Params& P, int sb, unsigned char* lds) {
;     ...
;       for (int s = 0; s < SC_CH; ++s) {
;         f32x4 w4n, k4n, b4n, kh4n, r4n; float vn;
;         if (s + 1 < SC_CH) {
;           const float* qn = q + (s + 1) * SC_STEP;
;           w4n = *(const f32x4*)(qn); k4n = *(const f32x4*)(qn + 64); b4n = *(const f32x4*)(qn + 128); kh4n = *(const f32x4*)(qn + 192); r4n = *(const f32x4*)(qn + 256);
;           vn = qv[(s + 1) * SC_STEP];
;         }
;         __builtin_amdgcn_sched_barrier(0);
;         if (s > 0) {
;           const float y = dpp_allreduce16(ypart);
;           yk = (ks == ((s - 1) & 15)) ? y : yk;
;           if (((s - 1) & 15) == 15) yo[(size_t)(s - 16) * 1024] = yk;
;         }
;         const f32x2 pp = (f32x2){S[0], S[1]} * (f32x2){k4[0], k4[1]} + (f32x2){S[2], S[3]} * (f32x2){k4[2], k4[3]};
;         const f32x4 A = S * w4 + v * kh4;
;         const float ar = dpp_allreduce16(pp.x + pp.y);
;         S = A + ar * b4;
;         const f32x2 yy = (f32x2){S[0], S[1]} * (f32x2){r4[0], r4[1]} + (f32x2){S[2], S[3]} * (f32x2){r4[2], r4[3]};
;         ypart = yy.x + yy.y;
;         if (s + 1 < SC_CH) { w4 = w4n; k4 = k4n; b4 = b4n; kh4 = kh4n; r4 = r4n; v = vn; }
	v_pk_mul_f32 v[52:53], v[6:7], v[14:15]
	v_pk_mul_f32 v[56:57], v[6:7], v[18:19]
	v_pk_fma_f32 v[52:53], v[4:5], v[12:13], v[52:53]
	v_pk_mul_f32 v[54:55], v[4:5], v[16:17]
	v_add_f32_e32 v52, v52, v53
	ds_read_b128 v[76:79], v9 offset:15040
	ds_read_b128 v[80:83], v9 offset:14784
	v_add_f32_dpp v52, v52, v52 quad_perm:[1,0,3,2] row_mask:0xf bank_mask:0xf bound_ctrl:1
	v_pk_fma_f32 v[56:57], v[22:23], v[24:25], v[56:57] op_sel_hi:[1,0,1]
	v_pk_fma_f32 v[54:55], v[20:21], v[24:25], v[54:55] op_sel_hi:[1,0,1]
	v_add_f32_dpp v52, v52, v52 quad_perm:[2,3,0,1] row_mask:0xf bank_mask:0xf bound_ctrl:1
	ds_read_b128 v[88:91], v9 offset:15552
	ds_read_b32 v94, v10 offset:16064
	v_add_f32_dpp v52, v52, v52 row_half_mirror row_mask:0xf bank_mask:0xf bound_ctrl:1
	v_pk_mul_f32 v[26:27], v[6:7], v[102:103]
	v_add_f32_dpp v34, v25, v25 row_ror:8 row_mask:0xf bank_mask:0x3
	v_add_f32_dpp v52, v52, v52 row_mirror row_mask:0xf bank_mask:0xf bound_ctrl:1
	v_pk_fma_f32 v[6:7], v[46:47], v[52:53], v[56:57] op_sel_hi:[1,0,1]
	v_pk_fma_f32 v[26:27], v[4:5], v[100:101], v[26:27]
	v_pk_fma_f32 v[4:5], v[44:45], v[52:53], v[54:55] op_sel_hi:[1,0,1]
	ds_read_b128 v[96:99], v9 offset:14464
	ds_read_b128 v[108:111], v9 offset:15296
	v_add_f32_e32 v25, v26, v27
	v_pk_mul_f32 v[52:53], v[6:7], v[62:63]
	v_pk_mul_f32 v[56:57], v[6:7], v[66:67]
	v_pk_fma_f32 v[52:53], v[4:5], v[60:61], v[52:53]
	v_pk_mul_f32 v[54:55], v[4:5], v[64:65]
	v_add_f32_e32 v52, v52, v53
	ds_read_b128 v[12:15], v9 offset:16384
	ds_read_b128 v[16:19], v9 offset:16128
	v_add_f32_dpp v52, v52, v52 quad_perm:[1,0,3,2] row_mask:0xf bank_mask:0xf bound_ctrl:1
	v_pk_fma_f32 v[56:57], v[30:31], v[32:33], v[56:57] op_sel_hi:[1,0,1]
	v_pk_fma_f32 v[54:55], v[28:29], v[32:33], v[54:55] op_sel_hi:[1,0,1]
	v_add_f32_dpp v52, v52, v52 quad_perm:[2,3,0,1] row_mask:0xf bank_mask:0xf bound_ctrl:1
	ds_read_b128 v[20:23], v9 offset:16896
	ds_read_b32 v24, v10 offset:17408
	v_add_f32_dpp v52, v52, v52 row_half_mirror row_mask:0xf bank_mask:0xf bound_ctrl:1
	v_pk_mul_f32 v[26:27], v[6:7], v[38:39]
	v_add_f32_dpp v34, v25, v25 row_ror:8 row_mask:0xf bank_mask:0xc
	v_add_f32_dpp v52, v52, v52 row_mirror row_mask:0xf bank_mask:0xf bound_ctrl:1
	v_pk_fma_f32 v[6:7], v[50:51], v[52:53], v[56:57] op_sel_hi:[1,0,1]
	v_pk_fma_f32 v[26:27], v[4:5], v[36:37], v[26:27]
	v_pk_fma_f32 v[4:5], v[48:49], v[52:53], v[54:55] op_sel_hi:[1,0,1]
	ds_read_b128 v[100:103], v9 offset:15808
	ds_read_b128 v[44:47], v9 offset:16640
	v_add_f32_e32 v25, v26, v27
	v_add_f32_dpp v58, v34, v34 row_half_mirror row_mask:0xf bank_mask:0xa
	s_waitcnt lgkmcnt(6)
	v_pk_mul_f32 v[52:53], v[6:7], v[70:71]
	v_pk_mul_f32 v[56:57], v[6:7], v[74:75]
	v_pk_fma_f32 v[52:53], v[4:5], v[68:69], v[52:53]
	v_pk_mul_f32 v[54:55], v[4:5], v[72:73]
	v_add_f32_e32 v52, v52, v53
	ds_read_b128 v[60:63], v9 offset:17728
	ds_read_b128 v[64:67], v9 offset:17472
	v_add_f32_dpp v52, v52, v52 quad_perm:[1,0,3,2] row_mask:0xf bank_mask:0xf bound_ctrl:1
	v_pk_fma_f32 v[56:57], v[86:87], v[92:93], v[56:57] op_sel_hi:[1,0,1]
	v_pk_fma_f32 v[54:55], v[84:85], v[92:93], v[54:55] op_sel_hi:[1,0,1]
	v_add_f32_dpp v52, v52, v52 quad_perm:[2,3,0,1] row_mask:0xf bank_mask:0xf bound_ctrl:1
	ds_read_b128 v[28:31], v9 offset:18240
	ds_read_b32 v32, v10 offset:18752
	v_add_f32_dpp v52, v52, v52 row_half_mirror row_mask:0xf bank_mask:0xf bound_ctrl:1
	v_pk_mul_f32 v[26:27], v[6:7], v[42:43]
	v_add_f32_dpp v34, v25, v25 row_ror:8 row_mask:0xf bank_mask:0x3
	v_add_f32_dpp v52, v52, v52 row_mirror row_mask:0xf bank_mask:0xf bound_ctrl:1
	v_pk_fma_f32 v[6:7], v[106:107], v[52:53], v[56:57] op_sel_hi:[1,0,1]
	v_pk_fma_f32 v[26:27], v[4:5], v[40:41], v[26:27]
	v_pk_fma_f32 v[4:5], v[104:105], v[52:53], v[54:55] op_sel_hi:[1,0,1]
	ds_read_b128 v[36:39], v9 offset:17152
	ds_read_b128 v[48:51], v9 offset:17984
	v_add_f32_e32 v25, v26, v27
	v_cndmask_b32_e64 v255, v35, v58, s[40:41]
	v_pk_mul_f32 v[52:53], v[6:7], v[78:79]
	v_pk_mul_f32 v[56:57], v[6:7], v[82:83]
	v_pk_fma_f32 v[52:53], v[4:5], v[76:77], v[52:53]
	v_pk_mul_f32 v[54:55], v[4:5], v[80:81]
	v_add_f32_e32 v52, v52, v53
	ds_read_b128 v[68:71], v9 offset:19072
	ds_read_b128 v[72:75], v9 offset:18816
	v_add_f32_dpp v52, v52, v52 quad_perm:[1,0,3,2] row_mask:0xf bank_mask:0xf bound_ctrl:1
	v_pk_fma_f32 v[56:57], v[90:91], v[94:95], v[56:57] op_sel_hi:[1,0,1]
	v_pk_fma_f32 v[54:55], v[88:89], v[94:95], v[54:55] op_sel_hi:[1,0,1]
	v_add_f32_dpp v52, v52, v52 quad_perm:[2,3,0,1] row_mask:0xf bank_mask:0xf bound_ctrl:1
	ds_read_b128 v[84:87], v9 offset:19584
	ds_read_b32 v92, v10 offset:20096
	v_add_f32_dpp v52, v52, v52 row_half_mirror row_mask:0xf bank_mask:0xf bound_ctrl:1
	v_pk_mul_f32 v[26:27], v[6:7], v[98:99]
	v_add_f32_dpp v34, v25, v25 row_ror:8 row_mask:0xf bank_mask:0xc
	v_add_f32_dpp v52, v52, v52 row_mirror row_mask:0xf bank_mask:0xf bound_ctrl:1
	v_pk_fma_f32 v[6:7], v[110:111], v[52:53], v[56:57] op_sel_hi:[1,0,1]
	v_pk_fma_f32 v[26:27], v[4:5], v[96:97], v[26:27]
	v_pk_fma_f32 v[4:5], v[108:109], v[52:53], v[54:55] op_sel_hi:[1,0,1]
	ds_read_b128 v[40:43], v9 offset:18496
	ds_read_b128 v[104:107], v9 offset:19328
	v_add_f32_e32 v25, v26, v27
	v_add_f32_dpp v0, v34, v34 row_half_mirror row_mask:0xf bank_mask:0x5
	s_waitcnt lgkmcnt(6)
; __device__ void scan_block(const Params& P, int sb, unsigned char* lds) {
;     ...
;       for (int s = 0; s < SC_CH; ++s) {
;         f32x4 w4n, k4n, b4n, kh4n, r4n; float vn;
;         if (s + 1 < SC_CH) {
;           const float* qn = q + (s + 1) * SC_STEP;
;           w4n = *(const f32x4*)(qn); k4n = *(const f32x4*)(qn + 64); b4n = *(const f32x4*)(qn + 128); kh4n = *(const f32x4*)(qn + 192); r4n = *(const f32x4*)(qn + 256);
;           vn = qv[(s + 1) * SC_STEP];
;         }
;         __builtin_amdgcn_sched_barrier(0);
;         if (s > 0) {
;           const float y = dpp_allreduce16(ypart);
;           yk = (ks == ((s - 1) & 15)) ? y : yk;
;           if (((s - 1) & 15) == 15) yo[(size_t)(s - 16) * 1024] = yk;
;         }
;         const f32x2 pp = (f32x2){S[0], S[1]} * (f32x2){k4[0], k4[1]} + (f32x2){S[2], S[3]} * (f32x2){k4[2], k4[3]};
;         const f32x4 A = S * w4 + v * kh4;
;         const float ar = dpp_allreduce16(pp.x + pp.y);
;         S = A + ar * b4;
;         const f32x2 yy = (f32x2){S[0], S[1]} * (f32x2){r4[0], r4[1]} + (f32x2){S[2], S[3]} * (f32x2){r4[2], r4[3]};
;         ypart = yy.x + yy.y;
;         if (s + 1 < SC_CH) { w4 = w4n; k4 = k4n; b4 = b4n; kh4 = kh4n; r4 = r4n; v = vn; }
	v_pk_mul_f32 v[52:53], v[6:7], v[14:15]
	v_pk_mul_f32 v[56:57], v[6:7], v[18:19]
	v_pk_fma_f32 v[52:53], v[4:5], v[12:13], v[52:53]
	v_pk_mul_f32 v[54:55], v[4:5], v[16:17]
	v_add_f32_e32 v52, v52, v53
	ds_read_b128 v[76:79], v9 offset:20416
	ds_read_b128 v[80:83], v9 offset:20160
	v_add_f32_dpp v52, v52, v52 quad_perm:[1,0,3,2] row_mask:0xf bank_mask:0xf bound_ctrl:1
	v_pk_fma_f32 v[56:57], v[22:23], v[24:25], v[56:57] op_sel_hi:[1,0,1]
	v_pk_fma_f32 v[54:55], v[20:21], v[24:25], v[54:55] op_sel_hi:[1,0,1]
	v_add_f32_dpp v52, v52, v52 quad_perm:[2,3,0,1] row_mask:0xf bank_mask:0xf bound_ctrl:1
	ds_read_b128 v[88:91], v9 offset:20928
	ds_read_b32 v94, v10 offset:21440
	v_add_f32_dpp v52, v52, v52 row_half_mirror row_mask:0xf bank_mask:0xf bound_ctrl:1
	v_pk_mul_f32 v[26:27], v[6:7], v[102:103]
	v_add_f32_dpp v34, v25, v25 row_ror:8 row_mask:0xf bank_mask:0x3
	v_add_f32_dpp v52, v52, v52 row_mirror row_mask:0xf bank_mask:0xf bound_ctrl:1
	v_pk_fma_f32 v[6:7], v[46:47], v[52:53], v[56:57] op_sel_hi:[1,0,1]
	v_pk_fma_f32 v[26:27], v[4:5], v[100:101], v[26:27]
	v_pk_fma_f32 v[4:5], v[44:45], v[52:53], v[54:55] op_sel_hi:[1,0,1]
	ds_read_b128 v[96:99], v9 offset:19840
	ds_read_b128 v[108:111], v9 offset:20672
	v_add_f32_e32 v25, v26, v27
	v_cndmask_b32_e64 v8, v58, v35, s[40:41]
	v_pk_mul_f32 v[52:53], v[6:7], v[62:63]
	v_pk_mul_f32 v[56:57], v[6:7], v[66:67]
	v_pk_fma_f32 v[52:53], v[4:5], v[60:61], v[52:53]
	v_pk_mul_f32 v[54:55], v[4:5], v[64:65]
	v_add_f32_e32 v52, v52, v53
	ds_read_b128 v[12:15], v9 offset:21760
	ds_read_b128 v[16:19], v9 offset:21504
	v_add_f32_dpp v52, v52, v52 quad_perm:[1,0,3,2] row_mask:0xf bank_mask:0xf bound_ctrl:1
	v_pk_fma_f32 v[56:57], v[30:31], v[32:33], v[56:57] op_sel_hi:[1,0,1]
	v_pk_fma_f32 v[54:55], v[28:29], v[32:33], v[54:55] op_sel_hi:[1,0,1]
	v_add_f32_dpp v52, v52, v52 quad_perm:[2,3,0,1] row_mask:0xf bank_mask:0xf bound_ctrl:1
	ds_read_b128 v[20:23], v9 offset:22272
	ds_read_b32 v24, v10 offset:22784
	v_add_f32_dpp v52, v52, v52 row_half_mirror row_mask:0xf bank_mask:0xf bound_ctrl:1
	v_pk_mul_f32 v[26:27], v[6:7], v[38:39]
	v_add_f32_dpp v34, v25, v25 row_ror:8 row_mask:0xf bank_mask:0xc
	v_add_f32_dpp v52, v52, v52 row_mirror row_mask:0xf bank_mask:0xf bound_ctrl:1
	v_pk_fma_f32 v[6:7], v[50:51], v[52:53], v[56:57] op_sel_hi:[1,0,1]
	v_pk_fma_f32 v[26:27], v[4:5], v[36:37], v[26:27]
	v_pk_fma_f32 v[4:5], v[48:49], v[52:53], v[54:55] op_sel_hi:[1,0,1]
	ds_read_b128 v[100:103], v9 offset:21184
	ds_read_b128 v[44:47], v9 offset:22016
	v_add_f32_e32 v25, v26, v27
	v_add_f32_dpp v0, v34, v34 row_half_mirror row_mask:0xf bank_mask:0xa
	s_waitcnt lgkmcnt(6)
	v_pk_mul_f32 v[52:53], v[6:7], v[70:71]
	v_pk_mul_f32 v[56:57], v[6:7], v[74:75]
	v_pk_fma_f32 v[52:53], v[4:5], v[68:69], v[52:53]
	v_pk_mul_f32 v[54:55], v[4:5], v[72:73]
	v_add_f32_e32 v52, v52, v53
	ds_read_b128 v[60:63], v9 offset:23104
	ds_read_b128 v[64:67], v9 offset:22848
	v_add_f32_dpp v52, v52, v52 quad_perm:[1,0,3,2] row_mask:0xf bank_mask:0xf bound_ctrl:1
	v_pk_fma_f32 v[56:57], v[86:87], v[92:93], v[56:57] op_sel_hi:[1,0,1]
	v_pk_fma_f32 v[54:55], v[84:85], v[92:93], v[54:55] op_sel_hi:[1,0,1]
	v_add_f32_dpp v52, v52, v52 quad_perm:[2,3,0,1] row_mask:0xf bank_mask:0xf bound_ctrl:1
	ds_read_b128 v[28:31], v9 offset:23616
	ds_read_b32 v32, v10 offset:24128
	v_add_f32_dpp v52, v52, v52 row_half_mirror row_mask:0xf bank_mask:0xf bound_ctrl:1
	v_pk_mul_f32 v[26:27], v[6:7], v[42:43]
	v_add_f32_dpp v34, v25, v25 row_ror:8 row_mask:0xf bank_mask:0x3
	v_add_f32_dpp v52, v52, v52 row_mirror row_mask:0xf bank_mask:0xf bound_ctrl:1
	v_pk_fma_f32 v[6:7], v[106:107], v[52:53], v[56:57] op_sel_hi:[1,0,1]
	v_pk_fma_f32 v[26:27], v[4:5], v[40:41], v[26:27]
	v_pk_fma_f32 v[4:5], v[104:105], v[52:53], v[54:55] op_sel_hi:[1,0,1]
	ds_read_b128 v[36:39], v9 offset:22528
	ds_read_b128 v[48:51], v9 offset:23360
	v_add_f32_e32 v25, v26, v27
	v_add_f32_dpp v253, v8, v255 quad_perm:[2,3,0,1] row_mask:0xf bank_mask:0xf bound_ctrl:1
	v_pk_mul_f32 v[52:53], v[6:7], v[78:79]
	v_pk_mul_f32 v[56:57], v[6:7], v[82:83]
	v_pk_fma_f32 v[52:53], v[4:5], v[76:77], v[52:53]
	v_pk_mul_f32 v[54:55], v[4:5], v[80:81]
	v_add_f32_e32 v52, v52, v53
	ds_read_b128 v[68:71], v9 offset:24448
	ds_read_b128 v[72:75], v9 offset:24192
	v_add_f32_dpp v52, v52, v52 quad_perm:[1,0,3,2] row_mask:0xf bank_mask:0xf bound_ctrl:1
	v_pk_fma_f32 v[56:57], v[90:91], v[94:95], v[56:57] op_sel_hi:[1,0,1]
	v_pk_fma_f32 v[54:55], v[88:89], v[94:95], v[54:55] op_sel_hi:[1,0,1]
	v_add_f32_dpp v52, v52, v52 quad_perm:[2,3,0,1] row_mask:0xf bank_mask:0xf bound_ctrl:1
	ds_read_b128 v[84:87], v9 offset:24960
	ds_read_b32 v92, v10 offset:25472
	v_add_f32_dpp v52, v52, v52 row_half_mirror row_mask:0xf bank_mask:0xf bound_ctrl:1
	v_pk_mul_f32 v[26:27], v[6:7], v[98:99]
	v_add_f32_dpp v34, v25, v25 row_ror:8 row_mask:0xf bank_mask:0xc
	v_add_f32_dpp v52, v52, v52 row_mirror row_mask:0xf bank_mask:0xf bound_ctrl:1
	v_pk_fma_f32 v[6:7], v[110:111], v[52:53], v[56:57] op_sel_hi:[1,0,1]
	v_pk_fma_f32 v[26:27], v[4:5], v[96:97], v[26:27]
	v_pk_fma_f32 v[4:5], v[108:109], v[52:53], v[54:55] op_sel_hi:[1,0,1]
	ds_read_b128 v[40:43], v9 offset:23872
	ds_read_b128 v[104:107], v9 offset:24704
	v_add_f32_e32 v25, v26, v27
	v_add_f32_dpp v11, v34, v34 row_half_mirror row_mask:0xf bank_mask:0x5
	s_waitcnt lgkmcnt(6)
; __device__ void scan_block(const Params& P, int sb, unsigned char* lds) {
;     ...
;       for (int s = 0; s < SC_CH; ++s) {
;         f32x4 w4n, k4n, b4n, kh4n, r4n; float vn;
;         if (s + 1 < SC_CH) {
;           const float* qn = q + (s + 1) * SC_STEP;
;           w4n = *(const f32x4*)(qn); k4n = *(const f32x4*)(qn + 64); b4n = *(const f32x4*)(qn + 128); kh4n = *(const f32x4*)(qn + 192); r4n = *(const f32x4*)(qn + 256);
;           vn = qv[(s + 1) * SC_STEP];
;         }
;         __builtin_amdgcn_sched_barrier(0);
;         if (s > 0) {
;           const float y = dpp_allreduce16(ypart);
;           yk = (ks == ((s - 1) & 15)) ? y : yk;
;           if (((s - 1) & 15) == 15) yo[(size_t)(s - 16) * 1024] = yk;
;         }
;         const f32x2 pp = (f32x2){S[0], S[1]} * (f32x2){k4[0], k4[1]} + (f32x2){S[2], S[3]} * (f32x2){k4[2], k4[3]};
;         const f32x4 A = S * w4 + v * kh4;
;         const float ar = dpp_allreduce16(pp.x + pp.y);
;         S = A + ar * b4;
;         const f32x2 yy = (f32x2){S[0], S[1]} * (f32x2){r4[0], r4[1]} + (f32x2){S[2], S[3]} * (f32x2){r4[2], r4[3]};
;         ypart = yy.x + yy.y;
;         if (s + 1 < SC_CH) { w4 = w4n; k4 = k4n; b4 = b4n; kh4 = kh4n; r4 = r4n; v = vn; }
	v_pk_mul_f32 v[52:53], v[6:7], v[14:15]
	v_pk_mul_f32 v[56:57], v[6:7], v[18:19]
	v_pk_fma_f32 v[52:53], v[4:5], v[12:13], v[52:53]
	v_pk_mul_f32 v[54:55], v[4:5], v[16:17]
	v_add_f32_e32 v52, v52, v53
	ds_read_b128 v[76:79], v9 offset:25792
	ds_read_b128 v[80:83], v9 offset:25536
	v_add_f32_dpp v52, v52, v52 quad_perm:[1,0,3,2] row_mask:0xf bank_mask:0xf bound_ctrl:1
	v_pk_fma_f32 v[56:57], v[22:23], v[24:25], v[56:57] op_sel_hi:[1,0,1]
	v_pk_fma_f32 v[54:55], v[20:21], v[24:25], v[54:55] op_sel_hi:[1,0,1]
	v_add_f32_dpp v52, v52, v52 quad_perm:[2,3,0,1] row_mask:0xf bank_mask:0xf bound_ctrl:1
	ds_read_b128 v[88:91], v9 offset:26304
	ds_read_b32 v94, v10 offset:26816
	v_add_f32_dpp v52, v52, v52 row_half_mirror row_mask:0xf bank_mask:0xf bound_ctrl:1
	v_pk_mul_f32 v[26:27], v[6:7], v[102:103]
	v_add_f32_dpp v34, v25, v25 row_ror:8 row_mask:0xf bank_mask:0x3
	v_add_f32_dpp v52, v52, v52 row_mirror row_mask:0xf bank_mask:0xf bound_ctrl:1
	v_pk_fma_f32 v[6:7], v[46:47], v[52:53], v[56:57] op_sel_hi:[1,0,1]
	v_pk_fma_f32 v[26:27], v[4:5], v[100:101], v[26:27]
	v_pk_fma_f32 v[4:5], v[44:45], v[52:53], v[54:55] op_sel_hi:[1,0,1]
	ds_read_b128 v[96:99], v9 offset:25216
	ds_read_b128 v[108:111], v9 offset:26048
	v_add_f32_e32 v25, v26, v27
	v_pk_mul_f32 v[52:53], v[6:7], v[62:63]
	v_pk_mul_f32 v[56:57], v[6:7], v[66:67]
	v_pk_fma_f32 v[52:53], v[4:5], v[60:61], v[52:53]
	v_pk_mul_f32 v[54:55], v[4:5], v[64:65]
	v_add_f32_e32 v52, v52, v53
	ds_read_b128 v[12:15], v9 offset:27136
	ds_read_b128 v[16:19], v9 offset:26880
	v_add_f32_dpp v52, v52, v52 quad_perm:[1,0,3,2] row_mask:0xf bank_mask:0xf bound_ctrl:1
	v_pk_fma_f32 v[56:57], v[30:31], v[32:33], v[56:57] op_sel_hi:[1,0,1]
	v_pk_fma_f32 v[54:55], v[28:29], v[32:33], v[54:55] op_sel_hi:[1,0,1]
	v_add_f32_dpp v52, v52, v52 quad_perm:[2,3,0,1] row_mask:0xf bank_mask:0xf bound_ctrl:1
	ds_read_b128 v[20:23], v9 offset:27648
	ds_read_b32 v24, v10 offset:28160
	v_add_f32_dpp v52, v52, v52 row_half_mirror row_mask:0xf bank_mask:0xf bound_ctrl:1
	v_pk_mul_f32 v[26:27], v[6:7], v[38:39]
	v_add_f32_dpp v34, v25, v25 row_ror:8 row_mask:0xf bank_mask:0xc
	v_add_f32_dpp v52, v52, v52 row_mirror row_mask:0xf bank_mask:0xf bound_ctrl:1
	v_pk_fma_f32 v[6:7], v[50:51], v[52:53], v[56:57] op_sel_hi:[1,0,1]
	v_pk_fma_f32 v[26:27], v[4:5], v[36:37], v[26:27]
	v_pk_fma_f32 v[4:5], v[48:49], v[52:53], v[54:55] op_sel_hi:[1,0,1]
	ds_read_b128 v[100:103], v9 offset:26560
	ds_read_b128 v[44:47], v9 offset:27392
	v_add_f32_e32 v25, v26, v27
	v_add_f32_dpp v11, v34, v34 row_half_mirror row_mask:0xf bank_mask:0xa
	s_waitcnt lgkmcnt(6)
	v_pk_mul_f32 v[52:53], v[6:7], v[70:71]
	v_pk_mul_f32 v[56:57], v[6:7], v[74:75]
	v_pk_fma_f32 v[52:53], v[4:5], v[68:69], v[52:53]
	v_pk_mul_f32 v[54:55], v[4:5], v[72:73]
	v_add_f32_e32 v52, v52, v53
	ds_read_b128 v[60:63], v9 offset:28480
	ds_read_b128 v[64:67], v9 offset:28224
	v_add_f32_dpp v52, v52, v52 quad_perm:[1,0,3,2] row_mask:0xf bank_mask:0xf bound_ctrl:1
	v_pk_fma_f32 v[56:57], v[86:87], v[92:93], v[56:57] op_sel_hi:[1,0,1]
	v_pk_fma_f32 v[54:55], v[84:85], v[92:93], v[54:55] op_sel_hi:[1,0,1]
	v_add_f32_dpp v52, v52, v52 quad_perm:[2,3,0,1] row_mask:0xf bank_mask:0xf bound_ctrl:1
	ds_read_b128 v[28:31], v9 offset:28992
	ds_read_b32 v32, v10 offset:29504
	v_add_f32_dpp v52, v52, v52 row_half_mirror row_mask:0xf bank_mask:0xf bound_ctrl:1
	v_pk_mul_f32 v[26:27], v[6:7], v[42:43]
	v_add_f32_dpp v34, v25, v25 row_ror:8 row_mask:0xf bank_mask:0x3
	v_add_f32_dpp v52, v52, v52 row_mirror row_mask:0xf bank_mask:0xf bound_ctrl:1
	v_pk_fma_f32 v[6:7], v[106:107], v[52:53], v[56:57] op_sel_hi:[1,0,1]
	v_pk_fma_f32 v[26:27], v[4:5], v[40:41], v[26:27]
	v_pk_fma_f32 v[4:5], v[104:105], v[52:53], v[54:55] op_sel_hi:[1,0,1]
	ds_read_b128 v[36:39], v9 offset:27904
	ds_read_b128 v[48:51], v9 offset:28736
	v_add_f32_e32 v25, v26, v27
	v_cndmask_b32_e64 v255, v0, v11, s[40:41]
	v_pk_mul_f32 v[52:53], v[6:7], v[78:79]
	v_pk_mul_f32 v[56:57], v[6:7], v[82:83]
	v_pk_fma_f32 v[52:53], v[4:5], v[76:77], v[52:53]
	v_pk_mul_f32 v[54:55], v[4:5], v[80:81]
	v_add_f32_e32 v52, v52, v53
	ds_read_b128 v[68:71], v9 offset:29824
	ds_read_b128 v[72:75], v9 offset:29568
	v_add_f32_dpp v52, v52, v52 quad_perm:[1,0,3,2] row_mask:0xf bank_mask:0xf bound_ctrl:1
	v_pk_fma_f32 v[56:57], v[90:91], v[94:95], v[56:57] op_sel_hi:[1,0,1]
	v_pk_fma_f32 v[54:55], v[88:89], v[94:95], v[54:55] op_sel_hi:[1,0,1]
	v_add_f32_dpp v52, v52, v52 quad_perm:[2,3,0,1] row_mask:0xf bank_mask:0xf bound_ctrl:1
	ds_read_b128 v[84:87], v9 offset:30336
	ds_read_b32 v92, v10 offset:30848
	v_add_f32_dpp v52, v52, v52 row_half_mirror row_mask:0xf bank_mask:0xf bound_ctrl:1
	v_pk_mul_f32 v[26:27], v[6:7], v[98:99]
	v_add_f32_dpp v34, v25, v25 row_ror:8 row_mask:0xf bank_mask:0xc
	v_add_f32_dpp v52, v52, v52 row_mirror row_mask:0xf bank_mask:0xf bound_ctrl:1
	v_pk_fma_f32 v[6:7], v[110:111], v[52:53], v[56:57] op_sel_hi:[1,0,1]
	v_pk_fma_f32 v[26:27], v[4:5], v[96:97], v[26:27]
	v_pk_fma_f32 v[4:5], v[108:109], v[52:53], v[54:55] op_sel_hi:[1,0,1]
	ds_read_b128 v[40:43], v9 offset:29248
	ds_read_b128 v[104:107], v9 offset:30080
	v_add_f32_e32 v25, v26, v27
	v_add_f32_dpp v35, v34, v34 row_half_mirror row_mask:0xf bank_mask:0x5
	s_waitcnt lgkmcnt(6)
; __device__ void scan_block(const Params& P, int sb, unsigned char* lds) {
;     ...
;       for (int s = 0; s < SC_CH; ++s) {
;         f32x4 w4n, k4n, b4n, kh4n, r4n; float vn;
;         if (s + 1 < SC_CH) {
;           const float* qn = q + (s + 1) * SC_STEP;
;           w4n = *(const f32x4*)(qn); k4n = *(const f32x4*)(qn + 64); b4n = *(const f32x4*)(qn + 128); kh4n = *(const f32x4*)(qn + 192); r4n = *(const f32x4*)(qn + 256);
;           vn = qv[(s + 1) * SC_STEP];
;         }
;         __builtin_amdgcn_sched_barrier(0);
;         if (s > 0) {
;           const float y = dpp_allreduce16(ypart);
;           yk = (ks == ((s - 1) & 15)) ? y : yk;
;           if (((s - 1) & 15) == 15) yo[(size_t)(s - 16) * 1024] = yk;
;         }
;         const f32x2 pp = (f32x2){S[0], S[1]} * (f32x2){k4[0], k4[1]} + (f32x2){S[2], S[3]} * (f32x2){k4[2], k4[3]};
;         const f32x4 A = S * w4 + v * kh4;
;         const float ar = dpp_allreduce16(pp.x + pp.y);
;         S = A + ar * b4;
;         const f32x2 yy = (f32x2){S[0], S[1]} * (f32x2){r4[0], r4[1]} + (f32x2){S[2], S[3]} * (f32x2){r4[2], r4[3]};
;         ypart = yy.x + yy.y;
;         if (s + 1 < SC_CH) { w4 = w4n; k4 = k4n; b4 = b4n; kh4 = kh4n; r4 = r4n; v = vn; }
	v_pk_mul_f32 v[52:53], v[6:7], v[14:15]
	v_pk_mul_f32 v[56:57], v[6:7], v[18:19]
	v_pk_fma_f32 v[52:53], v[4:5], v[12:13], v[52:53]
	v_pk_mul_f32 v[54:55], v[4:5], v[16:17]
	v_add_f32_e32 v52, v52, v53
	ds_read_b128 v[76:79], v9 offset:31168
	ds_read_b128 v[80:83], v9 offset:30912
	v_add_f32_dpp v52, v52, v52 quad_perm:[1,0,3,2] row_mask:0xf bank_mask:0xf bound_ctrl:1
	v_pk_fma_f32 v[56:57], v[22:23], v[24:25], v[56:57] op_sel_hi:[1,0,1]
	v_pk_fma_f32 v[54:55], v[20:21], v[24:25], v[54:55] op_sel_hi:[1,0,1]
	v_add_f32_dpp v52, v52, v52 quad_perm:[2,3,0,1] row_mask:0xf bank_mask:0xf bound_ctrl:1
	ds_read_b128 v[88:91], v9 offset:31680
	ds_read_b32 v94, v10 offset:32192
	v_add_f32_dpp v52, v52, v52 row_half_mirror row_mask:0xf bank_mask:0xf bound_ctrl:1
	v_pk_mul_f32 v[26:27], v[6:7], v[102:103]
	v_add_f32_dpp v34, v25, v25 row_ror:8 row_mask:0xf bank_mask:0x3
	v_add_f32_dpp v52, v52, v52 row_mirror row_mask:0xf bank_mask:0xf bound_ctrl:1
	v_pk_fma_f32 v[6:7], v[46:47], v[52:53], v[56:57] op_sel_hi:[1,0,1]
	v_pk_fma_f32 v[26:27], v[4:5], v[100:101], v[26:27]
	v_pk_fma_f32 v[4:5], v[44:45], v[52:53], v[54:55] op_sel_hi:[1,0,1]
	ds_read_b128 v[96:99], v9 offset:30592
	ds_read_b128 v[108:111], v9 offset:31424
	v_add_f32_e32 v25, v26, v27
	v_cndmask_b32_e64 v8, v11, v0, s[40:41]
	v_pk_mul_f32 v[52:53], v[6:7], v[62:63]
	v_pk_mul_f32 v[56:57], v[6:7], v[66:67]
	v_pk_fma_f32 v[52:53], v[4:5], v[60:61], v[52:53]
	v_pk_mul_f32 v[54:55], v[4:5], v[64:65]
	v_add_f32_e32 v52, v52, v53
	ds_read_b128 v[12:15], v9 offset:32512
	ds_read_b128 v[16:19], v9 offset:32256
	v_add_f32_dpp v52, v52, v52 quad_perm:[1,0,3,2] row_mask:0xf bank_mask:0xf bound_ctrl:1
	v_pk_fma_f32 v[56:57], v[30:31], v[32:33], v[56:57] op_sel_hi:[1,0,1]
	v_pk_fma_f32 v[54:55], v[28:29], v[32:33], v[54:55] op_sel_hi:[1,0,1]
	v_add_f32_dpp v52, v52, v52 quad_perm:[2,3,0,1] row_mask:0xf bank_mask:0xf bound_ctrl:1
	ds_read_b128 v[20:23], v9 offset:33024
	ds_read_b32 v24, v10 offset:33536
	v_add_f32_dpp v52, v52, v52 row_half_mirror row_mask:0xf bank_mask:0xf bound_ctrl:1
	v_pk_mul_f32 v[26:27], v[6:7], v[38:39]
	v_add_f32_dpp v34, v25, v25 row_ror:8 row_mask:0xf bank_mask:0xc
	v_add_f32_dpp v52, v52, v52 row_mirror row_mask:0xf bank_mask:0xf bound_ctrl:1
	v_pk_fma_f32 v[6:7], v[50:51], v[52:53], v[56:57] op_sel_hi:[1,0,1]
	v_pk_fma_f32 v[26:27], v[4:5], v[36:37], v[26:27]
	v_pk_fma_f32 v[4:5], v[48:49], v[52:53], v[54:55] op_sel_hi:[1,0,1]
	ds_read_b128 v[100:103], v9 offset:31936
	ds_read_b128 v[44:47], v9 offset:32768
	v_add_f32_e32 v25, v26, v27
	v_add_f32_dpp v35, v34, v34 row_half_mirror row_mask:0xf bank_mask:0xa
	s_waitcnt lgkmcnt(6)
	v_pk_mul_f32 v[52:53], v[6:7], v[70:71]
	v_pk_mul_f32 v[56:57], v[6:7], v[74:75]
	v_pk_fma_f32 v[52:53], v[4:5], v[68:69], v[52:53]
	v_pk_mul_f32 v[54:55], v[4:5], v[72:73]
	v_add_f32_e32 v52, v52, v53
	ds_read_b128 v[60:63], v9 offset:33856
	ds_read_b128 v[64:67], v9 offset:33600
	v_add_f32_dpp v52, v52, v52 quad_perm:[1,0,3,2] row_mask:0xf bank_mask:0xf bound_ctrl:1
	v_pk_fma_f32 v[56:57], v[86:87], v[92:93], v[56:57] op_sel_hi:[1,0,1]
	v_pk_fma_f32 v[54:55], v[84:85], v[92:93], v[54:55] op_sel_hi:[1,0,1]
	v_add_f32_dpp v52, v52, v52 quad_perm:[2,3,0,1] row_mask:0xf bank_mask:0xf bound_ctrl:1
	ds_read_b128 v[28:31], v9 offset:34368
	ds_read_b32 v32, v10 offset:34880
	v_add_f32_dpp v52, v52, v52 row_half_mirror row_mask:0xf bank_mask:0xf bound_ctrl:1
	v_pk_mul_f32 v[26:27], v[6:7], v[42:43]
	v_add_f32_dpp v34, v25, v25 row_ror:8 row_mask:0xf bank_mask:0x3
	v_add_f32_dpp v52, v52, v52 row_mirror row_mask:0xf bank_mask:0xf bound_ctrl:1
	v_pk_fma_f32 v[6:7], v[106:107], v[52:53], v[56:57] op_sel_hi:[1,0,1]
	v_pk_fma_f32 v[26:27], v[4:5], v[40:41], v[26:27]
	v_pk_fma_f32 v[4:5], v[104:105], v[52:53], v[54:55] op_sel_hi:[1,0,1]
	ds_read_b128 v[36:39], v9 offset:33280
	ds_read_b128 v[48:51], v9 offset:34112
	v_add_f32_e32 v25, v26, v27
	v_add_f32_dpp v254, v8, v255 quad_perm:[2,3,0,1] row_mask:0xf bank_mask:0xf bound_ctrl:1
	v_pk_mul_f32 v[52:53], v[6:7], v[78:79]
	v_pk_mul_f32 v[56:57], v[6:7], v[82:83]
	v_pk_fma_f32 v[52:53], v[4:5], v[76:77], v[52:53]
	v_pk_mul_f32 v[54:55], v[4:5], v[80:81]
	v_add_f32_e32 v52, v52, v53
	ds_read_b128 v[68:71], v9 offset:35200
	ds_read_b128 v[72:75], v9 offset:34944
	v_add_f32_dpp v52, v52, v52 quad_perm:[1,0,3,2] row_mask:0xf bank_mask:0xf bound_ctrl:1
	v_pk_fma_f32 v[56:57], v[90:91], v[94:95], v[56:57] op_sel_hi:[1,0,1]
	v_pk_fma_f32 v[54:55], v[88:89], v[94:95], v[54:55] op_sel_hi:[1,0,1]
	v_add_f32_dpp v52, v52, v52 quad_perm:[2,3,0,1] row_mask:0xf bank_mask:0xf bound_ctrl:1
	ds_read_b128 v[84:87], v9 offset:35712
	ds_read_b32 v92, v10 offset:36224
	v_add_f32_dpp v52, v52, v52 row_half_mirror row_mask:0xf bank_mask:0xf bound_ctrl:1
	v_pk_mul_f32 v[26:27], v[6:7], v[98:99]
	v_add_f32_dpp v34, v25, v25 row_ror:8 row_mask:0xf bank_mask:0xc
	v_add_f32_dpp v52, v52, v52 row_mirror row_mask:0xf bank_mask:0xf bound_ctrl:1
	v_pk_fma_f32 v[6:7], v[110:111], v[52:53], v[56:57] op_sel_hi:[1,0,1]
	v_pk_fma_f32 v[26:27], v[4:5], v[96:97], v[26:27]
	v_pk_fma_f32 v[4:5], v[108:109], v[52:53], v[54:55] op_sel_hi:[1,0,1]
	ds_read_b128 v[40:43], v9 offset:34624
	ds_read_b128 v[104:107], v9 offset:35456
	v_add_f32_e32 v25, v26, v27
	v_add_f32_dpp v58, v34, v34 row_half_mirror row_mask:0xf bank_mask:0x5
	s_waitcnt lgkmcnt(6)
; __device__ void scan_block(const Params& P, int sb, unsigned char* lds) {
;     ...
;       for (int s = 0; s < SC_CH; ++s) {
;         f32x4 w4n, k4n, b4n, kh4n, r4n; float vn;
;         if (s + 1 < SC_CH) {
;           const float* qn = q + (s + 1) * SC_STEP;
;           w4n = *(const f32x4*)(qn); k4n = *(const f32x4*)(qn + 64); b4n = *(const f32x4*)(qn + 128); kh4n = *(const f32x4*)(qn + 192); r4n = *(const f32x4*)(qn + 256);
;           vn = qv[(s + 1) * SC_STEP];
;         }
;         __builtin_amdgcn_sched_barrier(0);
;         if (s > 0) {
;           const float y = dpp_allreduce16(ypart);
;           yk = (ks == ((s - 1) & 15)) ? y : yk;
;           if (((s - 1) & 15) == 15) yo[(size_t)(s - 16) * 1024] = yk;
;         }
;         const f32x2 pp = (f32x2){S[0], S[1]} * (f32x2){k4[0], k4[1]} + (f32x2){S[2], S[3]} * (f32x2){k4[2], k4[3]};
;         const f32x4 A = S * w4 + v * kh4;
;         const float ar = dpp_allreduce16(pp.x + pp.y);
;         S = A + ar * b4;
;         const f32x2 yy = (f32x2){S[0], S[1]} * (f32x2){r4[0], r4[1]} + (f32x2){S[2], S[3]} * (f32x2){r4[2], r4[3]};
;         ypart = yy.x + yy.y;
;         if (s + 1 < SC_CH) { w4 = w4n; k4 = k4n; b4 = b4n; kh4 = kh4n; r4 = r4n; v = vn; }
	v_pk_mul_f32 v[52:53], v[6:7], v[14:15]
	v_pk_mul_f32 v[56:57], v[6:7], v[18:19]
	v_pk_fma_f32 v[52:53], v[4:5], v[12:13], v[52:53]
	v_pk_mul_f32 v[54:55], v[4:5], v[16:17]
	v_add_f32_e32 v52, v52, v53
	ds_read_b128 v[76:79], v9 offset:36544
	ds_read_b128 v[80:83], v9 offset:36288
	v_add_f32_dpp v52, v52, v52 quad_perm:[1,0,3,2] row_mask:0xf bank_mask:0xf bound_ctrl:1
	v_pk_fma_f32 v[56:57], v[22:23], v[24:25], v[56:57] op_sel_hi:[1,0,1]
	v_pk_fma_f32 v[54:55], v[20:21], v[24:25], v[54:55] op_sel_hi:[1,0,1]
	v_add_f32_dpp v52, v52, v52 quad_perm:[2,3,0,1] row_mask:0xf bank_mask:0xf bound_ctrl:1
	ds_read_b128 v[88:91], v9 offset:37056
	ds_read_b32 v94, v10 offset:37568
	v_add_f32_dpp v52, v52, v52 row_half_mirror row_mask:0xf bank_mask:0xf bound_ctrl:1
	v_pk_mul_f32 v[26:27], v[6:7], v[102:103]
	v_add_f32_dpp v34, v25, v25 row_ror:8 row_mask:0xf bank_mask:0x3
	v_add_f32_dpp v52, v52, v52 row_mirror row_mask:0xf bank_mask:0xf bound_ctrl:1
	v_pk_fma_f32 v[6:7], v[46:47], v[52:53], v[56:57] op_sel_hi:[1,0,1]
	v_pk_fma_f32 v[26:27], v[4:5], v[100:101], v[26:27]
	v_pk_fma_f32 v[4:5], v[44:45], v[52:53], v[54:55] op_sel_hi:[1,0,1]
	ds_read_b128 v[96:99], v9 offset:35968
	ds_read_b128 v[108:111], v9 offset:36800
	v_add_f32_e32 v25, v26, v27
	v_cndmask_b32_e64 v255, v253, v254, s[42:43]
	v_pk_mul_f32 v[52:53], v[6:7], v[62:63]
	v_pk_mul_f32 v[56:57], v[6:7], v[66:67]
	v_pk_fma_f32 v[52:53], v[4:5], v[60:61], v[52:53]
	v_pk_mul_f32 v[54:55], v[4:5], v[64:65]
	v_add_f32_e32 v52, v52, v53
	ds_read_b128 v[12:15], v9 offset:37888
	ds_read_b128 v[16:19], v9 offset:37632
	v_add_f32_dpp v52, v52, v52 quad_perm:[1,0,3,2] row_mask:0xf bank_mask:0xf bound_ctrl:1
	v_pk_fma_f32 v[56:57], v[30:31], v[32:33], v[56:57] op_sel_hi:[1,0,1]
	v_pk_fma_f32 v[54:55], v[28:29], v[32:33], v[54:55] op_sel_hi:[1,0,1]
	v_add_f32_dpp v52, v52, v52 quad_perm:[2,3,0,1] row_mask:0xf bank_mask:0xf bound_ctrl:1
	ds_read_b128 v[20:23], v9 offset:38400
	ds_read_b32 v24, v10 offset:38912
	v_add_f32_dpp v52, v52, v52 row_half_mirror row_mask:0xf bank_mask:0xf bound_ctrl:1
	v_pk_mul_f32 v[26:27], v[6:7], v[38:39]
	v_add_f32_dpp v34, v25, v25 row_ror:8 row_mask:0xf bank_mask:0xc
	v_add_f32_dpp v52, v52, v52 row_mirror row_mask:0xf bank_mask:0xf bound_ctrl:1
	v_pk_fma_f32 v[6:7], v[50:51], v[52:53], v[56:57] op_sel_hi:[1,0,1]
	v_pk_fma_f32 v[26:27], v[4:5], v[36:37], v[26:27]
	v_pk_fma_f32 v[4:5], v[48:49], v[52:53], v[54:55] op_sel_hi:[1,0,1]
	ds_read_b128 v[100:103], v9 offset:37312
	ds_read_b128 v[44:47], v9 offset:38144
	v_add_f32_e32 v25, v26, v27
	v_add_f32_dpp v58, v34, v34 row_half_mirror row_mask:0xf bank_mask:0xa
	s_waitcnt lgkmcnt(6)
	v_pk_mul_f32 v[52:53], v[6:7], v[70:71]
	v_pk_mul_f32 v[56:57], v[6:7], v[74:75]
	v_pk_fma_f32 v[52:53], v[4:5], v[68:69], v[52:53]
	v_pk_mul_f32 v[54:55], v[4:5], v[72:73]
	v_add_f32_e32 v52, v52, v53
	ds_read_b128 v[60:63], v9 offset:39232
	ds_read_b128 v[64:67], v9 offset:38976
	v_add_f32_dpp v52, v52, v52 quad_perm:[1,0,3,2] row_mask:0xf bank_mask:0xf bound_ctrl:1
	v_pk_fma_f32 v[56:57], v[86:87], v[92:93], v[56:57] op_sel_hi:[1,0,1]
	v_pk_fma_f32 v[54:55], v[84:85], v[92:93], v[54:55] op_sel_hi:[1,0,1]
	v_add_f32_dpp v52, v52, v52 quad_perm:[2,3,0,1] row_mask:0xf bank_mask:0xf bound_ctrl:1
	ds_read_b128 v[28:31], v9 offset:39744
	ds_read_b32 v32, v10 offset:40256
	v_add_f32_dpp v52, v52, v52 row_half_mirror row_mask:0xf bank_mask:0xf bound_ctrl:1
	v_pk_mul_f32 v[26:27], v[6:7], v[42:43]
	v_add_f32_dpp v34, v25, v25 row_ror:8 row_mask:0xf bank_mask:0x3
	v_add_f32_dpp v52, v52, v52 row_mirror row_mask:0xf bank_mask:0xf bound_ctrl:1
	v_pk_fma_f32 v[6:7], v[106:107], v[52:53], v[56:57] op_sel_hi:[1,0,1]
	v_pk_fma_f32 v[26:27], v[4:5], v[40:41], v[26:27]
	v_pk_fma_f32 v[4:5], v[104:105], v[52:53], v[54:55] op_sel_hi:[1,0,1]
	ds_read_b128 v[36:39], v9 offset:38656
	ds_read_b128 v[48:51], v9 offset:39488
	v_add_f32_e32 v25, v26, v27
	v_cndmask_b32_e64 v8, v254, v253, s[42:43]
	v_pk_mul_f32 v[52:53], v[6:7], v[78:79]
	v_pk_mul_f32 v[56:57], v[6:7], v[82:83]
	v_pk_fma_f32 v[52:53], v[4:5], v[76:77], v[52:53]
	v_pk_mul_f32 v[54:55], v[4:5], v[80:81]
	v_add_f32_e32 v52, v52, v53
	ds_read_b128 v[68:71], v9 offset:40576
	ds_read_b128 v[72:75], v9 offset:40320
	v_add_f32_dpp v52, v52, v52 quad_perm:[1,0,3,2] row_mask:0xf bank_mask:0xf bound_ctrl:1
	v_pk_fma_f32 v[56:57], v[90:91], v[94:95], v[56:57] op_sel_hi:[1,0,1]
	v_pk_fma_f32 v[54:55], v[88:89], v[94:95], v[54:55] op_sel_hi:[1,0,1]
	v_add_f32_dpp v52, v52, v52 quad_perm:[2,3,0,1] row_mask:0xf bank_mask:0xf bound_ctrl:1
	ds_read_b128 v[84:87], v9 offset:41088
	ds_read_b32 v92, v10 offset:41600
	v_add_f32_dpp v52, v52, v52 row_half_mirror row_mask:0xf bank_mask:0xf bound_ctrl:1
	v_pk_mul_f32 v[26:27], v[6:7], v[98:99]
	v_add_f32_dpp v34, v25, v25 row_ror:8 row_mask:0xf bank_mask:0xc
	v_add_f32_dpp v52, v52, v52 row_mirror row_mask:0xf bank_mask:0xf bound_ctrl:1
	v_pk_fma_f32 v[6:7], v[110:111], v[52:53], v[56:57] op_sel_hi:[1,0,1]
	v_pk_fma_f32 v[26:27], v[4:5], v[96:97], v[26:27]
	v_pk_fma_f32 v[4:5], v[108:109], v[52:53], v[54:55] op_sel_hi:[1,0,1]
	ds_read_b128 v[40:43], v9 offset:40000
	ds_read_b128 v[104:107], v9 offset:40832
	v_add_f32_e32 v25, v26, v27
	v_add_f32_dpp v0, v34, v34 row_half_mirror row_mask:0xf bank_mask:0x5
	s_waitcnt lgkmcnt(6)
; __device__ void scan_block(const Params& P, int sb, unsigned char* lds) {
;     ...
;       for (int s = 0; s < SC_CH; ++s) {
;         f32x4 w4n, k4n, b4n, kh4n, r4n; float vn;
;         if (s + 1 < SC_CH) {
;           const float* qn = q + (s + 1) * SC_STEP;
;           w4n = *(const f32x4*)(qn); k4n = *(const f32x4*)(qn + 64); b4n = *(const f32x4*)(qn + 128); kh4n = *(const f32x4*)(qn + 192); r4n = *(const f32x4*)(qn + 256);
;           vn = qv[(s + 1) * SC_STEP];
;         }
;         __builtin_amdgcn_sched_barrier(0);
;         if (s > 0) {
;           const float y = dpp_allreduce16(ypart);
;           yk = (ks == ((s - 1) & 15)) ? y : yk;
;           if (((s - 1) & 15) == 15) yo[(size_t)(s - 16) * 1024] = yk;
;         }
;         const f32x2 pp = (f32x2){S[0], S[1]} * (f32x2){k4[0], k4[1]} + (f32x2){S[2], S[3]} * (f32x2){k4[2], k4[3]};
;         const f32x4 A = S * w4 + v * kh4;
;         const float ar = dpp_allreduce16(pp.x + pp.y);
;         S = A + ar * b4;
;         const f32x2 yy = (f32x2){S[0], S[1]} * (f32x2){r4[0], r4[1]} + (f32x2){S[2], S[3]} * (f32x2){r4[2], r4[3]};
;         ypart = yy.x + yy.y;
;         if (s + 1 < SC_CH) { w4 = w4n; k4 = k4n; b4 = b4n; kh4 = kh4n; r4 = r4n; v = vn; }
;       }
;       { const float y = dpp_allreduce16(ypart); yk = (ks == 15) ? y : yk; yo[(size_t)16 * 1024] = yk; }
;       __syncthreads();
;     }
	v_pk_mul_f32 v[52:53], v[6:7], v[14:15]
	v_pk_mul_f32 v[56:57], v[6:7], v[18:19]
	v_pk_fma_f32 v[52:53], v[4:5], v[12:13], v[52:53]
	v_pk_mul_f32 v[54:55], v[4:5], v[16:17]
	v_add_f32_e32 v52, v52, v53
	ds_read_b128 v[76:79], v9 offset:41920
	ds_read_b128 v[80:83], v9 offset:41664
	v_add_f32_dpp v52, v52, v52 quad_perm:[1,0,3,2] row_mask:0xf bank_mask:0xf bound_ctrl:1
	v_pk_fma_f32 v[56:57], v[22:23], v[24:25], v[56:57] op_sel_hi:[1,0,1]
	v_pk_fma_f32 v[54:55], v[20:21], v[24:25], v[54:55] op_sel_hi:[1,0,1]
	v_add_f32_dpp v52, v52, v52 quad_perm:[2,3,0,1] row_mask:0xf bank_mask:0xf bound_ctrl:1
	ds_read_b128 v[88:91], v9 offset:42432
	ds_read_b32 v94, v10 offset:42944
	v_add_f32_dpp v52, v52, v52 row_half_mirror row_mask:0xf bank_mask:0xf bound_ctrl:1
	v_pk_mul_f32 v[26:27], v[6:7], v[102:103]
	v_add_f32_dpp v34, v25, v25 row_ror:8 row_mask:0xf bank_mask:0x3
	v_add_f32_dpp v52, v52, v52 row_mirror row_mask:0xf bank_mask:0xf bound_ctrl:1
	v_pk_fma_f32 v[6:7], v[46:47], v[52:53], v[56:57] op_sel_hi:[1,0,1]
	v_pk_fma_f32 v[26:27], v[4:5], v[100:101], v[26:27]
	v_pk_fma_f32 v[4:5], v[44:45], v[52:53], v[54:55] op_sel_hi:[1,0,1]
	ds_read_b128 v[96:99], v9 offset:41344
	ds_read_b128 v[108:111], v9 offset:42176
	v_add_f32_e32 v25, v26, v27
	v_add_f32_dpp v33, v8, v255 quad_perm:[1,0,3,2] row_mask:0xf bank_mask:0xf bound_ctrl:1
	v_pk_mul_f32 v[52:53], v[6:7], v[62:63]
	v_pk_mul_f32 v[56:57], v[6:7], v[66:67]
	v_pk_fma_f32 v[52:53], v[4:5], v[60:61], v[52:53]
	v_pk_mul_f32 v[54:55], v[4:5], v[64:65]
	v_add_f32_e32 v52, v52, v53
	s_nop 1
	v_add_f32_dpp v52, v52, v52 quad_perm:[1,0,3,2] row_mask:0xf bank_mask:0xf bound_ctrl:1
	v_pk_fma_f32 v[56:57], v[30:31], v[32:33], v[56:57] op_sel_hi:[1,0,1]
	v_pk_fma_f32 v[54:55], v[28:29], v[32:33], v[54:55] op_sel_hi:[1,0,1]
	v_add_f32_dpp v52, v52, v52 quad_perm:[2,3,0,1] row_mask:0xf bank_mask:0xf bound_ctrl:1
	s_nop 1
	v_add_f32_dpp v52, v52, v52 row_half_mirror row_mask:0xf bank_mask:0xf bound_ctrl:1
	v_pk_mul_f32 v[26:27], v[6:7], v[38:39]
	v_add_f32_dpp v34, v25, v25 row_ror:8 row_mask:0xf bank_mask:0xc
	v_add_f32_dpp v52, v52, v52 row_mirror row_mask:0xf bank_mask:0xf bound_ctrl:1
	v_pk_fma_f32 v[6:7], v[50:51], v[52:53], v[56:57] op_sel_hi:[1,0,1]
	v_pk_fma_f32 v[26:27], v[4:5], v[36:37], v[26:27]
	v_pk_fma_f32 v[4:5], v[48:49], v[52:53], v[54:55] op_sel_hi:[1,0,1]
	ds_read_b128 v[100:103], v9 offset:42688
	v_add_f32_e32 v25, v26, v27
	v_add_f32_dpp v0, v34, v34 row_half_mirror row_mask:0xf bank_mask:0xa
	s_waitcnt lgkmcnt(1)
	v_pk_mul_f32 v[52:53], v[6:7], v[70:71]
	v_pk_mul_f32 v[56:57], v[6:7], v[74:75]
	v_pk_fma_f32 v[52:53], v[4:5], v[68:69], v[52:53]
	v_pk_mul_f32 v[54:55], v[4:5], v[72:73]
	v_add_f32_e32 v52, v52, v53
	s_nop 1
	v_add_f32_dpp v52, v52, v52 quad_perm:[1,0,3,2] row_mask:0xf bank_mask:0xf bound_ctrl:1
	v_pk_fma_f32 v[56:57], v[86:87], v[92:93], v[56:57] op_sel_hi:[1,0,1]
	v_pk_fma_f32 v[54:55], v[84:85], v[92:93], v[54:55] op_sel_hi:[1,0,1]
	v_add_f32_dpp v52, v52, v52 quad_perm:[2,3,0,1] row_mask:0xf bank_mask:0xf bound_ctrl:1
	s_nop 1
	v_add_f32_dpp v52, v52, v52 row_half_mirror row_mask:0xf bank_mask:0xf bound_ctrl:1
	v_pk_mul_f32 v[26:27], v[6:7], v[42:43]
	v_add_f32_dpp v34, v25, v25 row_ror:8 row_mask:0xf bank_mask:0x3
	v_add_f32_dpp v52, v52, v52 row_mirror row_mask:0xf bank_mask:0xf bound_ctrl:1
	v_pk_fma_f32 v[6:7], v[106:107], v[52:53], v[56:57] op_sel_hi:[1,0,1]
	v_pk_fma_f32 v[26:27], v[4:5], v[40:41], v[26:27]
	v_pk_fma_f32 v[4:5], v[104:105], v[52:53], v[54:55] op_sel_hi:[1,0,1]
	v_add_f32_e32 v25, v26, v27
	global_store_dword v2, v33, s[4:5]
	v_pk_mul_f32 v[52:53], v[6:7], v[78:79]
	v_pk_mul_f32 v[56:57], v[6:7], v[82:83]
	v_pk_fma_f32 v[52:53], v[4:5], v[76:77], v[52:53]
	v_pk_mul_f32 v[54:55], v[4:5], v[80:81]
	v_add_f32_e32 v52, v52, v53
	s_nop 1
	v_add_f32_dpp v52, v52, v52 quad_perm:[1,0,3,2] row_mask:0xf bank_mask:0xf bound_ctrl:1
	v_pk_fma_f32 v[56:57], v[90:91], v[94:95], v[56:57] op_sel_hi:[1,0,1]
	v_pk_fma_f32 v[54:55], v[88:89], v[94:95], v[54:55] op_sel_hi:[1,0,1]
	v_add_f32_dpp v52, v52, v52 quad_perm:[2,3,0,1] row_mask:0xf bank_mask:0xf bound_ctrl:1
	s_nop 1
	v_add_f32_dpp v52, v52, v52 row_half_mirror row_mask:0xf bank_mask:0xf bound_ctrl:1
	v_pk_mul_f32 v[26:27], v[6:7], v[98:99]
	v_add_f32_dpp v34, v25, v25 row_ror:8 row_mask:0xf bank_mask:0xc
	v_add_f32_dpp v52, v52, v52 row_mirror row_mask:0xf bank_mask:0xf bound_ctrl:1
	v_pk_fma_f32 v[6:7], v[110:111], v[52:53], v[56:57] op_sel_hi:[1,0,1]
	v_pk_fma_f32 v[26:27], v[4:5], v[96:97], v[26:27]
	v_pk_fma_f32 v[4:5], v[108:109], v[52:53], v[54:55] op_sel_hi:[1,0,1]
	v_add_f32_e32 v25, v26, v27
	v_add_f32_dpp v11, v34, v34 row_half_mirror row_mask:0xf bank_mask:0x5
	s_waitcnt lgkmcnt(0)
	s_barrier
	v_xor_b32_e32 v9, 0xa800, v9
	v_xor_b32_e32 v10, 0xa800, v10
	ds_read_b128 v[12:15], v9 offset:256
	ds_read_b128 v[16:19], v9 offset:0
	v_add_f32_dpp v34, v25, v25 row_ror:8 row_mask:0xf bank_mask:0x3
	v_pk_mul_f32 v[26:27], v[6:7], v[102:103]
	ds_read_b128 v[20:23], v9 offset:768
	v_cndmask_b32_e64 v255, v35, v58, s[40:41]
	v_cndmask_b32_e64 v8, v58, v35, s[40:41]
	v_pk_fma_f32 v[26:27], v[4:5], v[100:101], v[26:27]
	ds_read_b32 v24, v10 offset:1280
	v_add_f32_e32 v25, v26, v27
	ds_read_b128 v[44:47], v9 offset:512
	v_add_f32_dpp v253, v8, v255 quad_perm:[2,3,0,1] row_mask:0xf bank_mask:0xf bound_ctrl:1
	v_add_f32_dpp v34, v25, v25 row_ror:8 row_mask:0xf bank_mask:0xc
	ds_read_b128 v[60:63], v9 offset:1600
	ds_read_b128 v[64:67], v9 offset:1344
	v_add_f32_dpp v11, v34, v34 row_half_mirror row_mask:0xf bank_mask:0xa
	ds_read_b128 v[28:31], v9 offset:2112
	ds_read_b32 v32, v10 offset:2624
	v_cndmask_b32_e64 v255, v0, v11, s[40:41]
	v_cndmask_b32_e64 v8, v11, v0, s[40:41]
	ds_read_b128 v[48:51], v9 offset:1856
	ds_read_b128 v[36:39], v9 offset:1024
	v_add_f32_dpp v254, v8, v255 quad_perm:[2,3,0,1] row_mask:0xf bank_mask:0xf bound_ctrl:1
	v_cndmask_b32_e64 v255, v253, v254, s[42:43]
	v_cndmask_b32_e64 v8, v254, v253, s[42:43]
	ds_read_b128 v[68:71], v9 offset:2944
	ds_read_b128 v[72:75], v9 offset:2688
	v_add_f32_dpp v33, v8, v255 quad_perm:[1,0,3,2] row_mask:0xf bank_mask:0xf bound_ctrl:1
	global_store_dword v3, v33, s[4:5]
	ds_read_b128 v[84:87], v9 offset:3456
	ds_read_b32 v92, v10 offset:3968
	ds_read_b128 v[104:107], v9 offset:3200
	ds_read_b128 v[40:43], v9 offset:2368
	s_add_i32 s3, s3, 1
	s_add_u32 s4, s4, 0x20000
	s_addc_u32 s5, s5, 0
	s_cmp_lg_u32 s3, 0x100
	s_cbranch_scc1 .Lscan_top
	s_waitcnt lgkmcnt(0)
	s_setprio 0
	v_readlane_b32 s60, v250, 1
	v_readlane_b32 s61, v250, 2
	s_mov_b64 s[62:63], s[90:91]
